# context-tile tails (out-proj, down-proj): gate/residual loads issued before the LDS reduce barrier, eight partial reads batched with counted waits
# speedup vs baseline: 1.0068x; 1.0026x over previous
.LBB0_1092:
	s_and_b32 s8, s13, 0xffffffe0
	s_ashr_i32 s9, s8, 31
	s_lshl_b64 s[10:11], s[8:9], 11
	v_lshl_add_u64 v[6:7], v[36:37], 0, s[10:11]
	s_lshl_b32 s10, s14, 2
	s_and_b32 s15, s10, 48
	s_lshl_b32 s10, s15, 1
	s_bfe_u32 s16, s14, 0x10001
	s_add_i32 s10, s10, s7
	s_lshl_b32 s17, s14, 6
	s_or_b32 s10, s10, s16
	s_ashr_i32 s11, s10, 31
	v_and_or_b32 v0, s17, 64, v44
	s_and_b32 s9, s17, 0x3c0
	s_lshl_b64 s[10:11], s[10:11], 14
	v_lshlrev_b32_e32 v55, 7, v0
	s_add_u32 s10, s3, s10
	v_or_b32_e32 v14, v55, v45
	v_or_b32_e32 v22, v55, v48
	s_addc_u32 s11, s6, s11
	v_or_b32_e32 v0, v14, v46
	v_bitop3_b32 v84, v14, 32, v47 bitop3:0x36
	v_or_b32_e32 v85, v22, v46
	v_bitop3_b32 v88, v22, 32, v47 bitop3:0x36
	v_add_co_u32_e32 v56, vcc, 0x2000000, v6
	v_and_b32_e32 v116, 15, v220
	v_bfe_u32 v117, v220, 4, 2
	v_addc_co_u32_e32 v57, vcc, 0, v7, vcc
	v_add_co_u32_e32 v58, vcc, 0x2008000, v6
	v_bfe_u32 v118, v116, 2, 1
	v_lshlrev_b32_e32 v118, 11, v118
	v_addc_co_u32_e32 v59, vcc, 0, v7, vcc
	v_lshrrev_b32_e32 v120, 3, v116
	v_lshl_or_b32 v118, v120, 8, v118
	v_and_b32_e32 v120, 3, v116
	v_lshl_or_b32 v118, v120, 6, v118
	v_lshl_or_b32 v84, v117, 4, v118
	v_xor_b32_e32 v85, 32, v84
	v_add_u32_e32 v85, 0x200, v85
	v_add_u32_e32 v86, 0x1000, v84
	v_add_u32_e32 v87, 0x1000, v85
	v_readfirstlane_b32 s15, v220
	s_and_b32 s17, s14, 15
	s_lshr_b32 s100, s17, 2
	s_lshl_b32 s100, s100, 19
	s_bfe_u32 s16, s17, 0x10001
	s_lshl_b32 s16, s16, 14
	s_add_i32 s100, s100, s16
	s_and_b32 s16, s17, 1
	s_lshl_b32 s16, s16, 13
	s_add_i32 s100, s100, s16
	s_lshr_b32 s15, s15, 6
	s_lshl_b32 s15, s15, 16
	s_add_i32 s100, s100, s15
	s_add_u32 s10, s3, s100
	s_addc_u32 s11, s6, 0
	global_load_dwordx4 v[72:75], v[56:57], off offset:0
	global_load_dwordx4 v[76:79], v[58:59], off offset:0
	global_load_dwordx4 v[80:83], v84, s[10:11]
	global_load_dwordx4 v[88:91], v85, s[10:11]
	global_load_dwordx4 v[92:95], v86, s[10:11]
	global_load_dwordx4 v[96:99], v87, s[10:11]
	s_add_u32 s10, s10, 0x400
	s_addc_u32 s11, s11, 0
	global_load_dwordx4 v[100:103], v[56:57], off offset:64
	global_load_dwordx4 v[104:107], v[58:59], off offset:64
	global_load_dwordx4 v[108:111], v84, s[10:11]
	global_load_dwordx4 v[112:115], v85, s[10:11]
	global_load_dwordx4 v[124:127], v86, s[10:11]
	global_load_dwordx4 v[128:131], v87, s[10:11]
	s_add_u32 s10, s10, 0x7c00
	s_addc_u32 s11, s11, 0
	global_load_dwordx4 v[132:135], v[56:57], off offset:128
	global_load_dwordx4 v[136:139], v[58:59], off offset:128
	global_load_dwordx4 v[140:143], v84, s[10:11]
	global_load_dwordx4 v[144:147], v85, s[10:11]
	global_load_dwordx4 v[148:151], v86, s[10:11]
	global_load_dwordx4 v[152:155], v87, s[10:11]
	s_add_u32 s10, s10, 0x400
	s_addc_u32 s11, s11, 0
	global_load_dwordx4 v[156:159], v[56:57], off offset:192
	global_load_dwordx4 v[160:163], v[58:59], off offset:192
	global_load_dwordx4 v[164:167], v84, s[10:11]
	global_load_dwordx4 v[168:171], v85, s[10:11]
	global_load_dwordx4 v[172:175], v86, s[10:11]
	global_load_dwordx4 v[176:179], v87, s[10:11]
	s_waitcnt vmcnt(18)
	v_mfma_f32_16x16x32_bf16 v[30:33], v[80:83], v[72:75], 0
	v_mfma_f32_16x16x32_bf16 v[26:29], v[88:91], v[72:75], 0
	v_mfma_f32_16x16x32_bf16 v[22:25], v[92:95], v[72:75], 0
	v_mfma_f32_16x16x32_bf16 v[18:21], v[96:99], v[72:75], 0
	v_mfma_f32_16x16x32_bf16 v[2:5], v[80:83], v[76:79], 0
	v_mfma_f32_16x16x32_bf16 v[6:9], v[88:91], v[76:79], 0
	v_mfma_f32_16x16x32_bf16 v[10:13], v[92:95], v[76:79], 0
	v_mfma_f32_16x16x32_bf16 v[14:17], v[96:99], v[76:79], 0
	s_waitcnt vmcnt(12)
	v_mfma_f32_16x16x32_bf16 v[30:33], v[108:111], v[100:103], v[30:33]
	v_mfma_f32_16x16x32_bf16 v[26:29], v[112:115], v[100:103], v[26:29]
	v_mfma_f32_16x16x32_bf16 v[22:25], v[124:127], v[100:103], v[22:25]
	v_mfma_f32_16x16x32_bf16 v[18:21], v[128:131], v[100:103], v[18:21]
	v_mfma_f32_16x16x32_bf16 v[2:5], v[108:111], v[104:107], v[2:5]
	v_mfma_f32_16x16x32_bf16 v[6:9], v[112:115], v[104:107], v[6:9]
	v_mfma_f32_16x16x32_bf16 v[10:13], v[124:127], v[104:107], v[10:13]
	v_mfma_f32_16x16x32_bf16 v[14:17], v[128:131], v[104:107], v[14:17]
	s_waitcnt vmcnt(6)
	v_mfma_f32_16x16x32_bf16 v[30:33], v[140:143], v[132:135], v[30:33]
	v_mfma_f32_16x16x32_bf16 v[26:29], v[144:147], v[132:135], v[26:29]
	v_mfma_f32_16x16x32_bf16 v[22:25], v[148:151], v[132:135], v[22:25]
	v_mfma_f32_16x16x32_bf16 v[18:21], v[152:155], v[132:135], v[18:21]
	v_mfma_f32_16x16x32_bf16 v[2:5], v[140:143], v[136:139], v[2:5]
	v_mfma_f32_16x16x32_bf16 v[6:9], v[144:147], v[136:139], v[6:9]
	v_mfma_f32_16x16x32_bf16 v[10:13], v[148:151], v[136:139], v[10:13]
	v_mfma_f32_16x16x32_bf16 v[14:17], v[152:155], v[136:139], v[14:17]
	s_waitcnt vmcnt(0)
	v_mfma_f32_16x16x32_bf16 v[30:33], v[164:167], v[156:159], v[30:33]
	v_mfma_f32_16x16x32_bf16 v[26:29], v[168:171], v[156:159], v[26:29]
	v_mfma_f32_16x16x32_bf16 v[22:25], v[172:175], v[156:159], v[22:25]
	v_mfma_f32_16x16x32_bf16 v[18:21], v[176:179], v[156:159], v[18:21]
	v_mfma_f32_16x16x32_bf16 v[2:5], v[164:167], v[160:163], v[2:5]
	v_mfma_f32_16x16x32_bf16 v[6:9], v[168:171], v[160:163], v[6:9]
	v_mfma_f32_16x16x32_bf16 v[10:13], v[172:175], v[160:163], v[10:13]
	v_mfma_f32_16x16x32_bf16 v[14:17], v[176:179], v[160:163], v[14:17]
	v_or_b32_e32 v0, s9, v52
	v_lshlrev_b32_e32 v0, 2, v0
	s_add_i32 s14, s14, s42
	s_add_i32 s13, s13, s68
	s_cmp_ge_i32 s14, s44
	ds_write_b128 v54, v[30:33]
	ds_write_b128 v54, v[26:29] offset:64
	ds_write_b128 v54, v[22:25] offset:128
	s_nop 0
	ds_write_b128 v54, v[18:21] offset:192
	ds_write_b128 v54, v[2:5] offset:4096
	ds_write_b128 v54, v[6:9] offset:4160
	ds_write_b128 v54, v[10:13] offset:4224
	ds_write_b128 v54, v[14:17] offset:4288
	v_add_u32_e32 v164, s8, v51
	v_ashrrev_i32_e32 v165, 31, v164
	v_lshlrev_b64 v[164:165], 12, v[164:165]
	v_lshl_add_u64 v[166:167], v[34:35], 0, v[164:165]
	v_lshl_add_u64 v[168:169], s[0:1], 0, v[164:165]
	v_lshl_add_u64 v[166:167], v[166:167], 0, v[0:1]
	v_lshl_add_u64 v[168:169], v[168:169], 0, v[0:1]
	global_load_dwordx4 v[156:159], v0, s[4:5]
	global_load_dwordx4 v[160:163], v[166:167], off
	s_waitcnt lgkmcnt(0)
	s_barrier
	ds_read_b128 v[124:127], v53
	ds_read_b128 v[128:131], v53 offset:8192
	ds_read_b128 v[132:135], v53 offset:16384
	ds_read_b128 v[136:139], v53 offset:24576
	ds_read_b128 v[140:143], v53 offset:32768
	ds_read_b128 v[144:147], v53 offset:40960
	ds_read_b128 v[148:151], v53 offset:49152
	ds_read_b128 v[152:155], v53 offset:57344
	s_waitcnt lgkmcnt(7)
	v_pk_add_f32 v[8:9], v[126:127], 0 op_sel_hi:[1,0]
	v_pk_add_f32 v[10:11], v[124:125], 0 op_sel_hi:[1,0]
	s_waitcnt lgkmcnt(6)
	v_pk_add_f32 v[8:9], v[8:9], v[130:131]
	v_pk_add_f32 v[10:11], v[10:11], v[128:129]
	s_waitcnt lgkmcnt(5)
	v_pk_add_f32 v[8:9], v[8:9], v[134:135]
	v_pk_add_f32 v[10:11], v[10:11], v[132:133]
	s_waitcnt lgkmcnt(4)
	v_pk_add_f32 v[8:9], v[8:9], v[138:139]
	v_pk_add_f32 v[10:11], v[10:11], v[136:137]
	s_waitcnt lgkmcnt(3)
	v_pk_add_f32 v[8:9], v[8:9], v[142:143]
	v_pk_add_f32 v[10:11], v[10:11], v[140:141]
	s_waitcnt lgkmcnt(2)
	v_pk_add_f32 v[8:9], v[8:9], v[146:147]
	v_pk_add_f32 v[10:11], v[10:11], v[144:145]
	s_waitcnt lgkmcnt(1)
	v_pk_add_f32 v[8:9], v[8:9], v[150:151]
	v_pk_add_f32 v[10:11], v[10:11], v[148:149]
	s_waitcnt lgkmcnt(0)
	v_pk_add_f32 v[12:13], v[8:9], v[154:155]
	v_pk_add_f32 v[10:11], v[10:11], v[152:153]
	s_waitcnt vmcnt(0)
	v_pk_fma_f32 v[2:3], v[10:11], v[156:157], v[160:161]
	v_pk_fma_f32 v[4:5], v[12:13], v[158:159], v[162:163]
	global_store_dwordx4 v[168:169], v[2:5], off
	s_barrier
	s_cbranch_scc0 .LBB0_1092

.LBB0_1464:
	s_and_b32 s16, s13, 0xffffffe0
	s_add_i32 s17, s16, 0x4000
	v_mov_b32_e32 v0, 0x1600
	v_mad_i64_i32 v[34:35], s[18:19], s17, v0, v[42:43]
	s_mov_b64 s[18:19], 0x16000
	s_and_b32 s15, s14, 15
	v_lshl_add_u64 v[38:39], v[34:35], 0, s[18:19]
	s_bfe_u32 s18, s14, 0x20002
	s_lshl_b32 s15, s15, 6
	s_mul_i32 s18, s18, 44
	s_add_i32 s19, s18, s2
	v_and_or_b32 v0, s15, 64, v44
	s_bfe_u32 s17, s14, 0x10001
	s_lshl_b32 s19, s19, 1
	v_lshrrev_b32_e32 v100, 3, v0
	s_or_b32 s20, s19, s17
	v_or_b32_e32 v0, s3, v100
	s_ashr_i32 s21, s20, 31
	v_lshl_or_b32 v0, v0, 10, v45
	v_or_b32_e32 v101, 4, v100
	s_lshl_b64 s[20:21], s[20:21], 14
	v_or_b32_e32 v71, v0, v46
	v_bitop3_b32 v69, v0, 32, v47 bitop3:0x36
	v_or_b32_e32 v0, s3, v101
	s_add_u32 s20, s4, s20
	v_lshl_or_b32 v0, v0, 10, v45
	s_addc_u32 s21, s5, s21
	v_or_b32_e32 v70, v0, v46
	v_bitop3_b32 v68, v0, 32, v48 bitop3:0x36
	v_and_b32_e32 v116, 15, v220
	v_bfe_u32 v117, v220, 4, 2
	v_bfe_u32 v118, v116, 2, 1
	v_lshlrev_b32_e32 v118, 11, v118
	v_lshrrev_b32_e32 v120, 3, v116
	v_lshl_or_b32 v118, v120, 8, v118
	v_and_b32_e32 v120, 3, v116
	v_lshl_or_b32 v118, v120, 6, v118
	v_lshl_or_b32 v84, v117, 4, v118
	v_xor_b32_e32 v85, 32, v84
	v_add_u32_e32 v85, 0x200, v85
	v_add_u32_e32 v86, 0x1000, v84
	v_add_u32_e32 v87, 0x1000, v85
	v_readfirstlane_b32 s20, v220
	s_and_b32 s17, s14, 15
	s_lshr_b32 s100, s17, 2
	s_mul_i32 s100, s100, 0x160000
	s_bfe_u32 s21, s17, 0x10001
	s_lshl_b32 s21, s21, 14
	s_add_i32 s100, s100, s21
	s_and_b32 s21, s17, 1
	s_lshl_b32 s21, s21, 13
	s_add_i32 s100, s100, s21
	s_lshr_b32 s20, s20, 6
	s_mul_i32 s20, s20, 11
	s_lshr_b32 s21, s20, 1
	s_lshl_b32 s21, s21, 15
	s_add_i32 s100, s100, s21
	s_and_b32 s21, s20, 1
	s_lshl_b32 s17, s21, 10
	s_add_i32 s100, s100, s17
	s_add_u32 s18, s4, s100
	s_addc_u32 s19, s5, 0
	s_movk_i32 s20, 0x400
	s_movk_i32 s17, 0x7c00
	s_cmp_eq_u32 s21, 0
	s_cselect_b32 s101, s20, s17
	s_cselect_b32 s17, s17, s20
	global_load_dwordx4 v[72:75], v[34:35], off offset:0
	global_load_dwordx4 v[76:79], v[38:39], off offset:0
	global_load_dwordx4 v[80:83], v84, s[18:19]
	global_load_dwordx4 v[88:91], v85, s[18:19]
	global_load_dwordx4 v[92:95], v86, s[18:19]
	global_load_dwordx4 v[96:99], v87, s[18:19]
	s_add_u32 s18, s18, s101
	s_addc_u32 s19, s19, 0
	global_load_dwordx4 v[100:103], v[34:35], off offset:64
	global_load_dwordx4 v[104:107], v[38:39], off offset:64
	global_load_dwordx4 v[108:111], v84, s[18:19]
	global_load_dwordx4 v[112:115], v85, s[18:19]
	global_load_dwordx4 v[124:127], v86, s[18:19]
	global_load_dwordx4 v[128:131], v87, s[18:19]
	s_add_u32 s18, s18, s17
	s_addc_u32 s19, s19, 0
	global_load_dwordx4 v[132:135], v[34:35], off offset:128
	global_load_dwordx4 v[136:139], v[38:39], off offset:128
	global_load_dwordx4 v[140:143], v84, s[18:19]
	global_load_dwordx4 v[144:147], v85, s[18:19]
	global_load_dwordx4 v[148:151], v86, s[18:19]
	global_load_dwordx4 v[152:155], v87, s[18:19]
	s_add_u32 s18, s18, s101
	s_addc_u32 s19, s19, 0
	global_load_dwordx4 v[156:159], v[34:35], off offset:192
	global_load_dwordx4 v[160:163], v[38:39], off offset:192
	global_load_dwordx4 v[164:167], v84, s[18:19]
	global_load_dwordx4 v[168:171], v85, s[18:19]
	global_load_dwordx4 v[172:175], v86, s[18:19]
	global_load_dwordx4 v[176:179], v87, s[18:19]
	s_add_u32 s18, s18, s17
	s_addc_u32 s19, s19, 0
	global_load_dwordx4 v[180:183], v[34:35], off offset:256
	global_load_dwordx4 v[184:187], v[38:39], off offset:256
	global_load_dwordx4 v[188:191], v84, s[18:19]
	global_load_dwordx4 v[192:195], v85, s[18:19]
	global_load_dwordx4 v[196:199], v86, s[18:19]
	global_load_dwordx4 v[200:203], v87, s[18:19]
	s_add_u32 s18, s18, s101
	s_addc_u32 s19, s19, 0
	s_waitcnt vmcnt(24)
	v_mfma_f32_16x16x32_bf16 v[30:33], v[80:83], v[72:75], 0
	v_mfma_f32_16x16x32_bf16 v[26:29], v[88:91], v[72:75], 0
	v_mfma_f32_16x16x32_bf16 v[22:25], v[92:95], v[72:75], 0
	v_mfma_f32_16x16x32_bf16 v[18:21], v[96:99], v[72:75], 0
	v_mfma_f32_16x16x32_bf16 v[2:5], v[80:83], v[76:79], 0
	v_mfma_f32_16x16x32_bf16 v[6:9], v[88:91], v[76:79], 0
	v_mfma_f32_16x16x32_bf16 v[10:13], v[92:95], v[76:79], 0
	v_mfma_f32_16x16x32_bf16 v[14:17], v[96:99], v[76:79], 0
	global_load_dwordx4 v[72:75], v[34:35], off offset:320
	global_load_dwordx4 v[76:79], v[38:39], off offset:320
	global_load_dwordx4 v[80:83], v84, s[18:19]
	global_load_dwordx4 v[88:91], v85, s[18:19]
	global_load_dwordx4 v[92:95], v86, s[18:19]
	global_load_dwordx4 v[96:99], v87, s[18:19]
	s_add_u32 s18, s18, s17
	s_addc_u32 s19, s19, 0
	s_waitcnt vmcnt(24)
	v_mfma_f32_16x16x32_bf16 v[30:33], v[108:111], v[100:103], v[30:33]
	v_mfma_f32_16x16x32_bf16 v[26:29], v[112:115], v[100:103], v[26:29]
	v_mfma_f32_16x16x32_bf16 v[22:25], v[124:127], v[100:103], v[22:25]
	v_mfma_f32_16x16x32_bf16 v[18:21], v[128:131], v[100:103], v[18:21]
	v_mfma_f32_16x16x32_bf16 v[2:5], v[108:111], v[104:107], v[2:5]
	v_mfma_f32_16x16x32_bf16 v[6:9], v[112:115], v[104:107], v[6:9]
	v_mfma_f32_16x16x32_bf16 v[10:13], v[124:127], v[104:107], v[10:13]
	v_mfma_f32_16x16x32_bf16 v[14:17], v[128:131], v[104:107], v[14:17]
	global_load_dwordx4 v[100:103], v[34:35], off offset:384
	global_load_dwordx4 v[104:107], v[38:39], off offset:384
	global_load_dwordx4 v[108:111], v84, s[18:19]
	global_load_dwordx4 v[112:115], v85, s[18:19]
	global_load_dwordx4 v[124:127], v86, s[18:19]
	global_load_dwordx4 v[128:131], v87, s[18:19]
	s_add_u32 s18, s18, s101
	s_addc_u32 s19, s19, 0
	s_waitcnt vmcnt(24)
	v_mfma_f32_16x16x32_bf16 v[30:33], v[140:143], v[132:135], v[30:33]
	v_mfma_f32_16x16x32_bf16 v[26:29], v[144:147], v[132:135], v[26:29]
	v_mfma_f32_16x16x32_bf16 v[22:25], v[148:151], v[132:135], v[22:25]
	v_mfma_f32_16x16x32_bf16 v[18:21], v[152:155], v[132:135], v[18:21]
	v_mfma_f32_16x16x32_bf16 v[2:5], v[140:143], v[136:139], v[2:5]
	v_mfma_f32_16x16x32_bf16 v[6:9], v[144:147], v[136:139], v[6:9]
	v_mfma_f32_16x16x32_bf16 v[10:13], v[148:151], v[136:139], v[10:13]
	v_mfma_f32_16x16x32_bf16 v[14:17], v[152:155], v[136:139], v[14:17]
	global_load_dwordx4 v[132:135], v[34:35], off offset:448
	global_load_dwordx4 v[136:139], v[38:39], off offset:448
	global_load_dwordx4 v[140:143], v84, s[18:19]
	global_load_dwordx4 v[144:147], v85, s[18:19]
	global_load_dwordx4 v[148:151], v86, s[18:19]
	global_load_dwordx4 v[152:155], v87, s[18:19]
	s_add_u32 s18, s18, s17
	s_addc_u32 s19, s19, 0
	s_waitcnt vmcnt(24)
	v_mfma_f32_16x16x32_bf16 v[30:33], v[164:167], v[156:159], v[30:33]
	v_mfma_f32_16x16x32_bf16 v[26:29], v[168:171], v[156:159], v[26:29]
	v_mfma_f32_16x16x32_bf16 v[22:25], v[172:175], v[156:159], v[22:25]
	v_mfma_f32_16x16x32_bf16 v[18:21], v[176:179], v[156:159], v[18:21]
	v_mfma_f32_16x16x32_bf16 v[2:5], v[164:167], v[160:163], v[2:5]
	v_mfma_f32_16x16x32_bf16 v[6:9], v[168:171], v[160:163], v[6:9]
	v_mfma_f32_16x16x32_bf16 v[10:13], v[172:175], v[160:163], v[10:13]
	v_mfma_f32_16x16x32_bf16 v[14:17], v[176:179], v[160:163], v[14:17]
	global_load_dwordx4 v[156:159], v[34:35], off offset:512
	global_load_dwordx4 v[160:163], v[38:39], off offset:512
	global_load_dwordx4 v[164:167], v84, s[18:19]
	global_load_dwordx4 v[168:171], v85, s[18:19]
	global_load_dwordx4 v[172:175], v86, s[18:19]
	global_load_dwordx4 v[176:179], v87, s[18:19]
	s_add_u32 s18, s18, s101
	s_addc_u32 s19, s19, 0
	s_waitcnt vmcnt(24)
	v_mfma_f32_16x16x32_bf16 v[30:33], v[188:191], v[180:183], v[30:33]
	v_mfma_f32_16x16x32_bf16 v[26:29], v[192:195], v[180:183], v[26:29]
	v_mfma_f32_16x16x32_bf16 v[22:25], v[196:199], v[180:183], v[22:25]
	v_mfma_f32_16x16x32_bf16 v[18:21], v[200:203], v[180:183], v[18:21]
	v_mfma_f32_16x16x32_bf16 v[2:5], v[188:191], v[184:187], v[2:5]
	v_mfma_f32_16x16x32_bf16 v[6:9], v[192:195], v[184:187], v[6:9]
	v_mfma_f32_16x16x32_bf16 v[10:13], v[196:199], v[184:187], v[10:13]
	v_mfma_f32_16x16x32_bf16 v[14:17], v[200:203], v[184:187], v[14:17]
	global_load_dwordx4 v[180:183], v[34:35], off offset:576
	global_load_dwordx4 v[184:187], v[38:39], off offset:576
	global_load_dwordx4 v[188:191], v84, s[18:19]
	global_load_dwordx4 v[192:195], v85, s[18:19]
	global_load_dwordx4 v[196:199], v86, s[18:19]
	global_load_dwordx4 v[200:203], v87, s[18:19]
	s_add_u32 s18, s18, s17
	s_addc_u32 s19, s19, 0
	s_waitcnt vmcnt(24)
	v_mfma_f32_16x16x32_bf16 v[30:33], v[80:83], v[72:75], v[30:33]
	v_mfma_f32_16x16x32_bf16 v[26:29], v[88:91], v[72:75], v[26:29]
	v_mfma_f32_16x16x32_bf16 v[22:25], v[92:95], v[72:75], v[22:25]
	v_mfma_f32_16x16x32_bf16 v[18:21], v[96:99], v[72:75], v[18:21]
	v_mfma_f32_16x16x32_bf16 v[2:5], v[80:83], v[76:79], v[2:5]
	v_mfma_f32_16x16x32_bf16 v[6:9], v[88:91], v[76:79], v[6:9]
	v_mfma_f32_16x16x32_bf16 v[10:13], v[92:95], v[76:79], v[10:13]
	v_mfma_f32_16x16x32_bf16 v[14:17], v[96:99], v[76:79], v[14:17]
	global_load_dwordx4 v[72:75], v[34:35], off offset:640
	global_load_dwordx4 v[76:79], v[38:39], off offset:640
	global_load_dwordx4 v[80:83], v84, s[18:19]
	global_load_dwordx4 v[88:91], v85, s[18:19]
	global_load_dwordx4 v[92:95], v86, s[18:19]
	global_load_dwordx4 v[96:99], v87, s[18:19]
	s_waitcnt vmcnt(24)
	v_mfma_f32_16x16x32_bf16 v[30:33], v[108:111], v[100:103], v[30:33]
	v_mfma_f32_16x16x32_bf16 v[26:29], v[112:115], v[100:103], v[26:29]
	v_mfma_f32_16x16x32_bf16 v[22:25], v[124:127], v[100:103], v[22:25]
	v_mfma_f32_16x16x32_bf16 v[18:21], v[128:131], v[100:103], v[18:21]
	v_mfma_f32_16x16x32_bf16 v[2:5], v[108:111], v[104:107], v[2:5]
	v_mfma_f32_16x16x32_bf16 v[6:9], v[112:115], v[104:107], v[6:9]
	v_mfma_f32_16x16x32_bf16 v[10:13], v[124:127], v[104:107], v[10:13]
	v_mfma_f32_16x16x32_bf16 v[14:17], v[128:131], v[104:107], v[14:17]
	s_waitcnt vmcnt(18)
	v_mfma_f32_16x16x32_bf16 v[30:33], v[140:143], v[132:135], v[30:33]
	v_mfma_f32_16x16x32_bf16 v[26:29], v[144:147], v[132:135], v[26:29]
	v_mfma_f32_16x16x32_bf16 v[22:25], v[148:151], v[132:135], v[22:25]
	v_mfma_f32_16x16x32_bf16 v[18:21], v[152:155], v[132:135], v[18:21]
	v_mfma_f32_16x16x32_bf16 v[2:5], v[140:143], v[136:139], v[2:5]
	v_mfma_f32_16x16x32_bf16 v[6:9], v[144:147], v[136:139], v[6:9]
	v_mfma_f32_16x16x32_bf16 v[10:13], v[148:151], v[136:139], v[10:13]
	v_mfma_f32_16x16x32_bf16 v[14:17], v[152:155], v[136:139], v[14:17]
	s_waitcnt vmcnt(12)
	v_mfma_f32_16x16x32_bf16 v[30:33], v[164:167], v[156:159], v[30:33]
	v_mfma_f32_16x16x32_bf16 v[26:29], v[168:171], v[156:159], v[26:29]
	v_mfma_f32_16x16x32_bf16 v[22:25], v[172:175], v[156:159], v[22:25]
	v_mfma_f32_16x16x32_bf16 v[18:21], v[176:179], v[156:159], v[18:21]
	v_mfma_f32_16x16x32_bf16 v[2:5], v[164:167], v[160:163], v[2:5]
	v_mfma_f32_16x16x32_bf16 v[6:9], v[168:171], v[160:163], v[6:9]
	v_mfma_f32_16x16x32_bf16 v[10:13], v[172:175], v[160:163], v[10:13]
	v_mfma_f32_16x16x32_bf16 v[14:17], v[176:179], v[160:163], v[14:17]
	s_waitcnt vmcnt(6)
	v_mfma_f32_16x16x32_bf16 v[30:33], v[188:191], v[180:183], v[30:33]
	v_mfma_f32_16x16x32_bf16 v[26:29], v[192:195], v[180:183], v[26:29]
	v_mfma_f32_16x16x32_bf16 v[22:25], v[196:199], v[180:183], v[22:25]
	v_mfma_f32_16x16x32_bf16 v[18:21], v[200:203], v[180:183], v[18:21]
	v_mfma_f32_16x16x32_bf16 v[2:5], v[188:191], v[184:187], v[2:5]
	v_mfma_f32_16x16x32_bf16 v[6:9], v[192:195], v[184:187], v[6:9]
	v_mfma_f32_16x16x32_bf16 v[10:13], v[196:199], v[184:187], v[10:13]
	v_mfma_f32_16x16x32_bf16 v[14:17], v[200:203], v[184:187], v[14:17]
	s_waitcnt vmcnt(0)
	v_mfma_f32_16x16x32_bf16 v[30:33], v[80:83], v[72:75], v[30:33]
	v_mfma_f32_16x16x32_bf16 v[26:29], v[88:91], v[72:75], v[26:29]
	v_mfma_f32_16x16x32_bf16 v[22:25], v[92:95], v[72:75], v[22:25]
	v_mfma_f32_16x16x32_bf16 v[18:21], v[96:99], v[72:75], v[18:21]
	v_mfma_f32_16x16x32_bf16 v[2:5], v[80:83], v[76:79], v[2:5]
	v_mfma_f32_16x16x32_bf16 v[6:9], v[88:91], v[76:79], v[6:9]
	v_mfma_f32_16x16x32_bf16 v[10:13], v[92:95], v[76:79], v[10:13]
	v_mfma_f32_16x16x32_bf16 v[14:17], v[96:99], v[76:79], v[14:17]
	v_or_b32_e32 v0, s15, v65
	v_lshlrev_b32_e32 v0, 2, v0
	s_add_i32 s14, s14, s42
	s_add_i32 s13, s13, s68
	s_cmp_ge_i32 s14, s44
	ds_write_b128 v67, v[30:33]
	ds_write_b128 v67, v[26:29] offset:64
	ds_write_b128 v67, v[22:25] offset:128
	s_nop 0
	ds_write_b128 v67, v[18:21] offset:192
	ds_write_b128 v67, v[2:5] offset:4096
	ds_write_b128 v67, v[6:9] offset:4160
	ds_write_b128 v67, v[10:13] offset:4224
	ds_write_b128 v67, v[14:17] offset:4288
	v_add_u32_e32 v164, s16, v64
	v_ashrrev_i32_e32 v165, 31, v164
	v_lshlrev_b64 v[164:165], 12, v[164:165]
	v_lshl_add_u64 v[166:167], s[0:1], 0, v[164:165]
	s_nop 0
	v_lshl_add_u64 v[166:167], v[166:167], 0, v[0:1]
	global_load_dwordx4 v[156:159], v0, s[8:9]
	global_load_dwordx4 v[160:163], v[166:167], off
	s_waitcnt lgkmcnt(0)
	s_barrier
	ds_read_b128 v[124:127], v66
	ds_read_b128 v[128:131], v66 offset:8192
	ds_read_b128 v[132:135], v66 offset:16384
	ds_read_b128 v[136:139], v66 offset:24576
	ds_read_b128 v[140:143], v66 offset:32768
	ds_read_b128 v[144:147], v66 offset:40960
	ds_read_b128 v[148:151], v66 offset:49152
	ds_read_b128 v[152:155], v66 offset:57344
	s_waitcnt lgkmcnt(7)
	v_pk_add_f32 v[8:9], v[126:127], 0 op_sel_hi:[1,0]
	v_pk_add_f32 v[10:11], v[124:125], 0 op_sel_hi:[1,0]
	s_waitcnt lgkmcnt(6)
	v_pk_add_f32 v[8:9], v[8:9], v[130:131]
	v_pk_add_f32 v[10:11], v[10:11], v[128:129]
	s_waitcnt lgkmcnt(5)
	v_pk_add_f32 v[8:9], v[8:9], v[134:135]
	v_pk_add_f32 v[10:11], v[10:11], v[132:133]
	s_waitcnt lgkmcnt(4)
	v_pk_add_f32 v[8:9], v[8:9], v[138:139]
	v_pk_add_f32 v[10:11], v[10:11], v[136:137]
	s_waitcnt lgkmcnt(3)
	v_pk_add_f32 v[8:9], v[8:9], v[142:143]
	v_pk_add_f32 v[10:11], v[10:11], v[140:141]
	s_waitcnt lgkmcnt(2)
	v_pk_add_f32 v[8:9], v[8:9], v[146:147]
	v_pk_add_f32 v[10:11], v[10:11], v[144:145]
	s_waitcnt lgkmcnt(1)
	v_pk_add_f32 v[8:9], v[8:9], v[150:151]
	v_pk_add_f32 v[10:11], v[10:11], v[148:149]
	s_waitcnt lgkmcnt(0)
	v_pk_add_f32 v[12:13], v[8:9], v[154:155]
	v_pk_add_f32 v[10:11], v[10:11], v[152:153]
	s_waitcnt vmcnt(0)
	v_pk_fma_f32 v[4:5], v[12:13], v[158:159], v[162:163]
	v_pk_fma_f32 v[2:3], v[10:11], v[156:157], v[160:161]
	global_store_dwordx4 v[166:167], v[2:5], off
	s_barrier
	s_cbranch_scc0 .LBB0_1464
